# NSA selected loop: step-1 K-fragment and tile-index LDS reads issued before the step-0 end barrier (overlap with row-sum adds); rescale-decision branch chain shortened in step 0 of selected/window loo
# speedup vs baseline: 1.0108x; 1.0051x over previous
; #define NS_GLOAD(k_, KR, VR) do { const int jj = __builtin_amdgcn_readfirstlane(jl[(k_)]); KR = *(const u32x4*)(kg + (size_t)(64 * jj + sr) * pitch + sc * 8); VR = *(const u32x4*)(vg + (size_t)(64 * jj + sr) * pitch + sc * 8); } while (0)
; #define NS_LSTORE(st_, KR, VR) do { lds8* b = lds + (st_) * NS_STAGE; *(LAS u32x4*)(b + sr * NS_STR + sc * 16) = KR; *(LAS u32x4*)(b + 64 * NS_STR + sr * NS_STR + sc * 16) = VR; } while (0)
; template <int NDVB, bool HAS_NEXT> DI void softmax_def(f32x16& sa0, f32x16& sa1, f32x16& sb0, f32x16& sb1, f32x16 (&O)[NDVB], float& muse, float& l, bool first, bf16x8 (&P)[4], bool check = true) {
;     ...
;   float sum = 0.f;
; #pragma unroll
;   for (int i = 0; i < 16; ++i) { sa0[i] = __builtin_amdgcn_exp2f(sa0[i]); sum += sa0[i]; }
; #pragma unroll
;   for (int i = 0; i < 16; ++i) { sa1[i] = __builtin_amdgcn_exp2f(sa1[i]); sum += sa1[i]; }
;   l += sum;
; template <int MODE>
; DI void nsa_branch(lds8* lds, const bf16_t* kg, const bf16_t* vg, int pitch, unsigned tiles, const bf16x8 (&q)[4], int qpos, unsigned mybits, int blk,
;                    f32x16 (&O)[2], float& muse, float& l, int tid, int lane, int grp, CmpCap& cap) {
;     ...
;   NS_GLOAD(0, kra, vra); NS_LSTORE(0, kra, vra);
;   if (ntl > 1) { NS_GLOAD(1, kra, vra); NS_LSTORE(1, kra, vra); }
;   __syncthreads();
;   f32x16 s0, s1, du0, du1; bf16x8 P[4];
;   int st_cur = 0;
.LBB0_951:
	v_exp_f32_e32 v108, v60
	v_add_u32_e32 v60, s95, v216
	v_exp_f32_e32 v96, v48
	v_exp_f32_e32 v97, v49
	v_exp_f32_e32 v98, v50
	v_exp_f32_e32 v99, v51
	v_exp_f32_e32 v100, v52
	v_exp_f32_e32 v101, v53
	v_exp_f32_e32 v102, v54
	v_exp_f32_e32 v103, v55
	v_exp_f32_e32 v104, v56
	v_exp_f32_e32 v105, v57
	v_exp_f32_e32 v106, v58
	v_exp_f32_e32 v107, v59
	v_exp_f32_e32 v124, v44
	v_exp_f32_e32 v125, v45
	v_exp_f32_e32 v126, v46
	v_exp_f32_e32 v127, v47
	ds_read_b64_tr_b16 v[44:45], v60 offset:9216
	ds_read_b64_tr_b16 v[46:47], v60 offset:10368
	ds_read_b64_tr_b16 v[50:51], v60 offset:10432
	ds_read_b64_tr_b16 v[48:49], v60 offset:9280
	ds_read_b64_tr_b16 v[52:53], v60 offset:11520
	ds_read_b64_tr_b16 v[54:55], v60 offset:12672
	ds_read_b64_tr_b16 v[58:59], v60 offset:12736
	ds_read_b64_tr_b16 v[56:57], v60 offset:11584
	v_exp_f32_e32 v109, v61
	v_exp_f32_e32 v110, v62
	v_exp_f32_e32 v111, v63
	v_exp_f32_e32 v112, v32
	v_exp_f32_e32 v113, v33
	v_exp_f32_e32 v114, v34
	v_exp_f32_e32 v115, v35
	v_exp_f32_e32 v116, v36
	v_exp_f32_e32 v117, v37
	v_exp_f32_e32 v118, v38
	v_exp_f32_e32 v119, v39
	v_exp_f32_e32 v120, v40
	v_exp_f32_e32 v121, v41
	v_exp_f32_e32 v122, v42
	v_exp_f32_e32 v123, v43
	v_cvt_pk_bf16_f32 v32, v96, v97
	v_cvt_pk_bf16_f32 v33, v98, v99
	v_cvt_pk_bf16_f32 v34, v100, v101
	v_cvt_pk_bf16_f32 v35, v102, v103
	v_cvt_pk_bf16_f32 v36, v104, v105
	v_cvt_pk_bf16_f32 v37, v106, v107
	v_cvt_pk_bf16_f32 v38, v108, v109
	v_cvt_pk_bf16_f32 v39, v110, v111
	v_cvt_pk_bf16_f32 v40, v112, v113
	v_cvt_pk_bf16_f32 v41, v114, v115
	v_cvt_pk_bf16_f32 v42, v116, v117
	v_cvt_pk_bf16_f32 v43, v118, v119
	v_cvt_pk_bf16_f32 v140, v120, v121
	v_cvt_pk_bf16_f32 v141, v122, v123
	v_cvt_pk_bf16_f32 v142, v124, v125
	v_cvt_pk_bf16_f32 v143, v126, v127
	s_setprio 1
	s_waitcnt lgkmcnt(6)
	v_mfma_f32_32x32x16_bf16 v[0:15], v[44:47], v[32:35], v[0:15]
	s_waitcnt lgkmcnt(4)
	v_mfma_f32_32x32x16_bf16 v[16:31], v[48:51], v[32:35], v[16:31]
	s_setprio 0
	ds_read_b64_tr_b16 v[32:33], v60 offset:13824
	ds_read_b64_tr_b16 v[34:35], v60 offset:14976
	ds_read_b64_tr_b16 v[46:47], v60 offset:15040
	ds_read_b64_tr_b16 v[44:45], v60 offset:13888
	s_setprio 1
	s_waitcnt lgkmcnt(6)
	v_mfma_f32_32x32x16_bf16 v[0:15], v[52:55], v[36:39], v[0:15]
	s_waitcnt lgkmcnt(4)
	v_mfma_f32_32x32x16_bf16 v[16:31], v[56:59], v[36:39], v[16:31]
	s_setprio 0
	ds_read_b64_tr_b16 v[48:49], v60 offset:16128
	ds_read_b64_tr_b16 v[50:51], v60 offset:17280
	ds_read_b64_tr_b16 v[146:147], v60 offset:17344
	ds_read_b64_tr_b16 v[144:145], v60 offset:16192
	s_setprio 1
	s_waitcnt lgkmcnt(6)
	v_mfma_f32_32x32x16_bf16 v[0:15], v[32:35], v[40:43], v[0:15]
	s_waitcnt lgkmcnt(4)
	v_mfma_f32_32x32x16_bf16 v[16:31], v[44:47], v[40:43], v[16:31]
	s_setprio 0
	s_setprio 1
	s_waitcnt lgkmcnt(2)
	v_mfma_f32_32x32x16_bf16 v[0:15], v[48:51], v[140:143], v[0:15]
	s_waitcnt lgkmcnt(0)
	v_mfma_f32_32x32x16_bf16 v[16:31], v[144:147], v[140:143], v[16:31]
	s_setprio 0
	s_andn2_b64 vcc, exec, s[82:83]
	s_cbranch_vccnz .LBB0_953
	s_addk_i32 s94, 0xb800
	s_cmp_lg_u32 s6, 0
	s_cselect_b32 s82, s94, 0x9000
	v_add_u32_e32 v234, s82, v215
	s_waitcnt vmcnt(1)
	ds_write_b128 v234, v[128:131]
	s_waitcnt vmcnt(0)
	ds_write_b128 v234, v[132:135] offset:9216
.LBB0_953:
	s_add_i32 s86, s6, 1
	s_cmp_lg_u32 s6, 2
	s_cselect_b32 s86, s86, 0
	s_mul_i32 s86, s86, 0x4800
	v_mov_b32_e32 v140, s90
	v_add_u32_e32 v60, s86, v213
	ds_read_b32 v232, v140 offset:12
	ds_read_b32 v233, v140 offset:4
	ds_read_b128 v[32:35], v60 offset:4608
	ds_read_b128 v[36:39], v60
	ds_read_b128 v[40:43], v60 offset:32
	ds_read_b128 v[44:47], v60 offset:4640
	ds_read_b128 v[48:51], v60 offset:64
	ds_read_b128 v[52:55], v60 offset:4672
	ds_read_b128 v[56:59], v60 offset:96
	ds_read_b128 v[60:63], v60 offset:4704
	v_add_f32_e32 v234, 0, v96
	v_add_f32_e32 v234, v97, v234
	v_add_f32_e32 v234, v98, v234
	v_add_f32_e32 v234, v99, v234
	v_add_f32_e32 v234, v100, v234
	v_add_f32_e32 v234, v101, v234
	v_add_f32_e32 v234, v102, v234
	v_add_f32_e32 v234, v103, v234
	v_add_f32_e32 v234, v104, v234
	v_add_f32_e32 v234, v105, v234
	v_add_f32_e32 v234, v106, v234
	v_add_f32_e32 v234, v107, v234
	v_add_f32_e32 v234, v108, v234
	v_add_f32_e32 v234, v109, v234
	v_add_f32_e32 v234, v110, v234
	v_add_f32_e32 v234, v111, v234
	v_add_f32_e32 v234, v112, v234
	v_add_f32_e32 v234, v113, v234
	v_add_f32_e32 v234, v114, v234
	v_add_f32_e32 v234, v115, v234
	v_add_f32_e32 v234, v116, v234
	v_add_f32_e32 v234, v117, v234
	v_add_f32_e32 v234, v118, v234
	v_add_f32_e32 v234, v119, v234
	v_add_f32_e32 v234, v120, v234
	v_add_f32_e32 v234, v121, v234
	v_add_f32_e32 v234, v122, v234
	v_add_f32_e32 v234, v123, v234
	v_add_f32_e32 v234, v124, v234
	v_add_f32_e32 v234, v125, v234
	v_add_f32_e32 v234, v126, v234
	v_add_f32_e32 v234, v127, v234
	s_add_i32 s84, s89, -2
	v_add_f32_e32 v139, v219, v234
	s_mov_b64 s[82:83], -1
	s_cmp_ge_u32 s84, s88
	s_mov_b64 s[84:85], -1
	s_movk_i32 s95, 0x1ff
	s_waitcnt lgkmcnt(0)
	s_barrier
	s_cbranch_scc1 .LBB0_937
	s_cmp_lt_u32 s89, s88
	s_cselect_b64 s[82:83], -1, 0
	s_add_i32 s84, s6, 1
	s_cmp_lg_u32 s6, 2
	s_cselect_b32 s6, s84, 0
	s_mul_i32 s86, s6, 0x4800
	s_add_i32 s87, s86, 0
	s_cmp_ge_u32 s89, s88
	s_cbranch_scc1 .Lslc1_noload
	s_waitcnt lgkmcnt(9)
	v_readfirstlane_b32 s84, v232
	s_nop 1
	v_lshl_add_u32 v228, s84, 6, v212
	v_ashrrev_i32_e32 v229, 31, v228
	v_lshlrev_b64 v[228:229], 9, v[228:229]
	v_lshl_add_u64 v[230:231], v[194:195], 0, v[228:229]
	v_lshl_add_u64 v[228:229], v[196:197], 0, v[228:229]
	global_load_dwordx4 v[128:131], v[230:231], off
	global_load_dwordx4 v[132:135], v[228:229], off
